# rope k-copy branch: both ushort loads issued before the first wait (one memory round trip instead of two), on top of 2-deep PV
# speedup vs baseline: 1.0015x; 1.0015x over previous
; __device__ __forceinline__ void prep_rope(Frame& F, const Args& a, int idx, int nwg) {
;     ...
;             if (p >= 128 && p < 160) { const int gg = (p >> 4) - 8; bf16_t* k2 = (bf16_t*)(F.ws + WS_KV2) + ((size_t)t * 2 + gg) * 256; k2[i] = ur[UK + 128 * gg + i]; k2[i + 16] = ur[UK + 128 * gg + i + 16]; }
.LBB0_773:
	s_or_b64 exec, exec, s[16:17]
	v_and_b32_e32 v10, 0xe0, v22
	v_cmp_eq_u32_e32 vcc, s49, v10
	s_and_saveexec_b64 s[16:17], vcc
	s_cbranch_execz .LBB0_766
	v_lshrrev_b32_e32 v10, 4, v22
	v_add_u32_e32 v22, -8, v10
	v_lshl_or_b32 v10, v22, 7, v0
	v_mov_b32_e32 v11, v1
	v_lshl_add_u64 v[8:9], v[10:11], 1, v[8:9]
	v_add_co_u32_e32 v8, vcc, 0x2000, v8
	v_lshlrev_b64 v[6:7], 10, v[6:7]
	s_nop 0
	v_addc_co_u32_e32 v9, vcc, 0, v9, vcc
	global_load_ushort v23, v[8:9], off offset:512
	global_load_ushort v27, v[8:9], off offset:544
	v_lshl_add_u64 v[6:7], s[24:25], 0, v[6:7]
	v_lshlrev_b32_e32 v10, 9, v22
	v_lshl_add_u64 v[6:7], v[6:7], 0, v[10:11]
	v_lshl_add_u64 v[6:7], v[0:1], 1, v[6:7]
	s_waitcnt vmcnt(1)
	global_store_short v[6:7], v23, off
	s_waitcnt vmcnt(1)
	global_store_short v[6:7], v27, off offset:32
	s_branch .LBB0_766
